# mixer A softmax denominator by ten 16x16x32 MFMAs on the bf16 P fragments (49 VALU adds + cross-half exchange removed)
# speedup vs baseline: 1.0069x; 1.0024x over previous
; #define LAS __attribute__((address_space(3)))
; #define MFMA32(a, b, c) __builtin_amdgcn_mfma_f32_32x32x16_bf16((a), (b), (c), 0, 0, 0)
; __device__ __forceinline__ s16x4 lds_tr(const LAS unsigned char* p) { return __builtin_bit_cast(s16x4, __builtin_amdgcn_ds_read_tr16_b64_v4i16((LAS v4i16_t*)p)); }
; __device__ __forceinline__ void attnA_unit(LAS unsigned char* lds, const Args& A, int unit) {
;     ...
;                 float lsp[2] = {0.f, 0.f};
; #pragma unroll
;                 for (int kt = 0; kt < 5; ++kt)
; #pragma unroll
;                     for (int i = 0; i < 16; ++i) { const float p = __builtin_amdgcn_exp2f(S[kt][i] - mx); S[kt][i] = p; lsp[i & 1] += p; }
;                 float ls = lsp[0] + lsp[1];
;                 ls += __shfl_xor(ls, 32);
;                 f32x16 o0, o1;
; #pragma unroll
;                 for (int i = 0; i < 16; ++i) { o0[i] = 0.f; o1[i] = 0.f; }
;                 const LAS unsigned char* vr0 = vt_l + (rb + 4 * hh + ((lane & 15) >> 2)) * AST + 32 * ((lane >> 4) & 1) + 8 * (lane & 3);
; #pragma unroll
;                 for (int kt = 0; kt < 5; ++kt)
; #pragma unroll
;                     for (int ks = 0; ks < 2; ++ks) {
;                         const bf16x8 pf = pack_frag(S[kt], ks);
;                         const LAS unsigned char* vr = vr0 + (32 * kt + 16 * ks) * AST;
;                         const s16x4 a0 = lds_tr(vr), a1 = lds_tr(vr + 8 * AST), c0 = lds_tr(vr + 64), c1 = lds_tr(vr + 8 * AST + 64);
;                         o0 = MFMA32(__builtin_shufflevector(a0, a1, 0, 1, 2, 3, 4, 5, 6, 7), pf, o0);
;                         o1 = MFMA32(__builtin_shufflevector(c0, c1, 0, 1, 2, 3, 4, 5, 6, 7), pf, o1);
.LmixA_join:
	v_lshrrev_b32_e32 v253, 1, v217
	v_xor_b32_e32 v253, v253, v217
	v_and_b32_e32 v253, 8, v253
	v_cmp_eq_u32_e32 vcc, 0, v253
	v_mov_b32_e32 v249, 0x3f803f80
	v_and_b32_e32 v253, 31, v217
	v_and_b32_e32 v250, 16, v217
	v_cndmask_b32_e32 v248, 0, v249, vcc
	v_add_lshl_u32 v253, v253, v250, 2
	v_mov_b32_e32 v249, v248
	v_mov_b32_e32 v250, v248
	v_mov_b32_e32 v251, v248
	v_and_b32_e32 v2, 64, v217
	v_xor_b32_e32 v1, 32, v217
	v_add_u32_e32 v2, 64, v2
	v_cmp_lt_i32_e32 vcc, v1, v2
	v_lshlrev_b32_e32 v32, v206, v164
	s_nop 0
	v_cndmask_b32_e32 v1, v217, v1, vcc
	v_lshlrev_b32_e32 v238, 2, v1
	ds_bpermute_b32 v1, v238, v0
	s_waitcnt lgkmcnt(0)
	v_max_f32_e32 v1, v1, v1
	v_max_f32_e32 v229, v0, v1
	v_mul_f32_e32 v229, 0x3e38aa3b, v229
	v_mov_b32_e32 v252, 0x3e38aa3b
	v_fma_f32 v10, v76, v252, -v229
	v_exp_f32_e32 v172, v10
	v_fma_f32 v10, v77, v252, -v229
	v_exp_f32_e32 v173, v10
	v_fma_f32 v10, v78, v252, -v229
	v_exp_f32_e32 v174, v10
	v_fma_f32 v10, v79, v252, -v229
	v_exp_f32_e32 v175, v10
	v_fma_f32 v10, v48, v252, -v229
	v_fma_f32 v8, v72, v252, -v229
	v_exp_f32_e32 v72, v10
	v_fma_f32 v10, v49, v252, -v229
	v_exp_f32_e32 v166, v8
	v_fma_f32 v8, v73, v252, -v229
	v_exp_f32_e32 v73, v10
	v_fma_f32 v10, v50, v252, -v229
	v_exp_f32_e32 v167, v8
	v_fma_f32 v8, v74, v252, -v229
	v_exp_f32_e32 v74, v10
	v_fma_f32 v10, v51, v252, -v229
	v_exp_f32_e32 v75, v10
	v_fma_f32 v10, v52, v252, -v229
	v_exp_f32_e32 v76, v10
	v_fma_f32 v10, v53, v252, -v229
	v_exp_f32_e32 v77, v10
	v_fma_f32 v10, v54, v252, -v229
	v_exp_f32_e32 v78, v10
	v_fma_f32 v10, v55, v252, -v229
	v_exp_f32_e32 v79, v10
	v_fma_f32 v10, v56, v252, -v229
	v_exp_f32_e32 v62, v10
	v_fma_f32 v10, v57, v252, -v229
	v_exp_f32_e32 v63, v10
	v_fma_f32 v10, v58, v252, -v229
	v_fma_f32 v2, v66, v252, -v229
	v_exp_f32_e32 v66, v10
	v_fma_f32 v10, v59, v252, -v229
	v_fma_f32 v0, v64, v252, -v229
	v_fma_f32 v1, v65, v252, -v229
	v_fma_f32 v3, v67, v252, -v229
	v_exp_f32_e32 v67, v10
	v_fma_f32 v10, v60, v252, -v229
	v_exp_f32_e32 v0, v0
	v_exp_f32_e32 v1, v1
	v_fma_f32 v4, v68, v252, -v229
	v_exp_f32_e32 v68, v10
	v_fma_f32 v10, v61, v252, -v229
	v_exp_f32_e32 v2, v2
	v_exp_f32_e32 v3, v3
	v_fma_f32 v5, v69, v252, -v229
	v_exp_f32_e32 v69, v10
	v_fma_f32 v10, v169, v252, -v229
	v_exp_f32_e32 v4, v4
	v_exp_f32_e32 v5, v5
	v_fma_f32 v6, v70, v252, -v229
	v_fma_f32 v7, v71, v252, -v229
	v_exp_f32_e32 v70, v10
	v_fma_f32 v10, v208, v252, -v229
	v_exp_f32_e32 v6, v6
	v_exp_f32_e32 v7, v7
	v_exp_f32_e32 v170, v8
	v_fma_f32 v8, v168, v252, -v229
	v_exp_f32_e32 v71, v10
	v_fma_f32 v10, v209, v252, -v229
	v_exp_f32_e32 v171, v8
	v_exp_f32_e32 v54, v10
	v_fma_f32 v10, v33, v252, -v229
	v_exp_f32_e32 v55, v10
	v_fma_f32 v10, v34, v252, -v229
	v_exp_f32_e32 v58, v10
	v_fma_f32 v10, v35, v252, -v229
	v_exp_f32_e32 v59, v10
	v_fma_f32 v10, v36, v252, -v229
	v_exp_f32_e32 v60, v10
	v_fma_f32 v10, v37, v252, -v229
	v_exp_f32_e32 v61, v10
	v_fma_f32 v10, v38, v252, -v229
	v_exp_f32_e32 v64, v10
	v_fma_f32 v10, v39, v252, -v229
	v_exp_f32_e32 v65, v10
	v_fma_f32 v10, v40, v252, -v229
	v_exp_f32_e32 v48, v10
	v_fma_f32 v10, v41, v252, -v229
	v_exp_f32_e32 v49, v10
	v_fma_f32 v10, v42, v252, -v229
	v_exp_f32_e32 v50, v10
	v_fma_f32 v10, v43, v252, -v229
	v_exp_f32_e32 v51, v10
	v_fma_f32 v10, v44, v252, -v229
	v_exp_f32_e32 v52, v10
	v_fma_f32 v10, v45, v252, -v229
	v_exp_f32_e32 v53, v10
	v_fma_f32 v10, v46, v252, -v229
	v_exp_f32_e32 v56, v10
	v_fma_f32 v10, v47, v252, -v229
	v_exp_f32_e32 v57, v10
	v_fma_f32 v10, v16, v252, -v229
	v_exp_f32_e32 v38, v10
	v_fma_f32 v10, v17, v252, -v229
	v_exp_f32_e32 v39, v10
	v_fma_f32 v10, v18, v252, -v229
	v_exp_f32_e32 v40, v10
	v_fma_f32 v10, v19, v252, -v229
	v_exp_f32_e32 v41, v10
	v_fma_f32 v10, v20, v252, -v229
	v_exp_f32_e32 v42, v10
	v_fma_f32 v10, v21, v252, -v229
	v_exp_f32_e32 v43, v10
	v_fma_f32 v10, v22, v252, -v229
	v_exp_f32_e32 v44, v10
	v_fma_f32 v10, v23, v252, -v229
	v_exp_f32_e32 v45, v10
	v_fma_f32 v12, v27, v252, -v229
	v_cvt_pk_bf16_f32 v16, v0, v1
	v_cvt_pk_bf16_f32 v17, v2, v3
	v_cvt_pk_bf16_f32 v18, v4, v5
	v_fma_f32 v8, v24, v252, -v229
	v_exp_f32_e32 v34, v8
	v_fma_f32 v8, v25, v252, -v229
	v_exp_f32_e32 v35, v8
	v_fma_f32 v8, v26, v252, -v229
	v_exp_f32_e32 v36, v8
	v_add_u32_e32 v8, v180, v163
	v_mad_u64_u32 v[246:247], s[22:23], v8, s88, v[152:153]
	ds_read_b64_tr_b16 v[8:9], v246 offset:59392
	ds_read_b64_tr_b16 v[10:11], v246 offset:60544
	v_cvt_pk_bf16_f32 v19, v6, v7
	v_exp_f32_e32 v37, v12
	v_fma_f32 v24, v28, v252, -v229
	ds_read_b64_tr_b16 v[20:21], v246 offset:59456
	ds_read_b64_tr_b16 v[22:23], v246 offset:60608
	s_waitcnt lgkmcnt(2)
	v_mfma_f32_32x32x16_bf16 v[0:15], v[8:11], v[16:19], 0
	v_mfma_f32_16x16x32_bf16 v[186:189], v[248:251], v[16:19], 0
	v_exp_f32_e32 v164, v24
	v_fma_f32 v24, v29, v252, -v229
	ds_read_b64_tr_b16 v[208:209], v246 offset:61696
	ds_read_b64_tr_b16 v[210:211], v246 offset:62848
	v_exp_f32_e32 v165, v24
	v_fma_f32 v24, v30, v252, -v229
	v_exp_f32_e32 v168, v24
	v_cvt_pk_bf16_f32 v242, v166, v167
	s_waitcnt lgkmcnt(2)
	v_mfma_f32_32x32x16_bf16 v[16:31], v[20:23], v[16:19], 0
	v_cvt_pk_bf16_f32 v243, v170, v171
	v_cvt_pk_bf16_f32 v244, v172, v173
	v_cvt_pk_bf16_f32 v245, v174, v175
	ds_read_b64_tr_b16 v[170:171], v246 offset:61760
	ds_read_b64_tr_b16 v[172:173], v246 offset:62912
	v_add_u32_e32 v163, 0xe800, v246
	v_cvt_pk_bf16_f32 v48, v48, v49
	v_cvt_pk_bf16_f32 v49, v50, v51
	s_waitcnt lgkmcnt(2)
; #define LAS __attribute__((address_space(3)))
; #define MFMA32(a, b, c) __builtin_amdgcn_mfma_f32_32x32x16_bf16((a), (b), (c), 0, 0, 0)
; __device__ __forceinline__ s16x4 lds_tr(const LAS unsigned char* p) { return __builtin_bit_cast(s16x4, __builtin_amdgcn_ds_read_tr16_b64_v4i16((LAS v4i16_t*)p)); }
; __device__ __forceinline__ void attnA_unit(LAS unsigned char* lds, const Args& A, int unit) {
;     ...
;                 const LAS unsigned char* vr0 = vt_l + (rb + 4 * hh + ((lane & 15) >> 2)) * AST + 32 * ((lane >> 4) & 1) + 8 * (lane & 3);
; #pragma unroll
;                 for (int kt = 0; kt < 5; ++kt)
; #pragma unroll
;                     for (int ks = 0; ks < 2; ++ks) {
;                         const bf16x8 pf = pack_frag(S[kt], ks);
;                         const LAS unsigned char* vr = vr0 + (32 * kt + 16 * ks) * AST;
;                         const s16x4 a0 = lds_tr(vr), a1 = lds_tr(vr + 8 * AST), c0 = lds_tr(vr + 64), c1 = lds_tr(vr + 8 * AST + 64);
;                         o0 = MFMA32(__builtin_shufflevector(a0, a1, 0, 1, 2, 3, 4, 5, 6, 7), pf, o0);
;                         o1 = MFMA32(__builtin_shufflevector(c0, c1, 0, 1, 2, 3, 4, 5, 6, 7), pf, o1);
;                     }
	v_mfma_f32_32x32x16_bf16 v[0:15], v[208:211], v[242:245], v[0:15]
	v_mfma_f32_16x16x32_bf16 v[186:189], v[248:251], v[242:245], v[186:189]
	ds_read_b64_tr_b16 v[208:209], v246 offset:64000
	ds_read_b64_tr_b16 v[210:211], v246 offset:65152
	v_cvt_pk_bf16_f32 v50, v52, v53
	v_cvt_pk_bf16_f32 v51, v56, v57
	v_fma_f32 v33, v224, v252, -v229
	v_exp_f32_e32 v169, v33
	v_fma_f32 v33, v223, v252, -v229
	v_cvt_pk_bf16_f32 v38, v38, v39
	s_waitcnt lgkmcnt(2)
	v_mfma_f32_32x32x16_bf16 v[16:31], v[170:173], v[242:245], v[16:31]
	v_cvt_pk_bf16_f32 v170, v72, v73
	v_cvt_pk_bf16_f32 v171, v74, v75
	v_cvt_pk_bf16_f32 v172, v76, v77
	v_cvt_pk_bf16_f32 v173, v78, v79
	ds_read_b64_tr_b16 v[74:75], v246 offset:64064
	ds_read_b64_tr_b16 v[76:77], v246 offset:65216
	v_cvt_pk_bf16_f32 v78, v68, v69
	v_cvt_pk_bf16_f32 v79, v70, v71
	s_waitcnt lgkmcnt(2)
	v_mfma_f32_32x32x16_bf16 v[0:15], v[208:211], v[170:173], v[0:15]
	v_mfma_f32_16x16x32_bf16 v[186:189], v[248:251], v[170:173], v[186:189]
	ds_read_b64_tr_b16 v[208:209], v163 offset:6912
	ds_read_b64_tr_b16 v[210:211], v163 offset:8064
	v_cvt_pk_bf16_f32 v39, v40, v41
	v_cvt_pk_bf16_f32 v40, v42, v43
	v_cvt_pk_bf16_f32 v41, v44, v45
	v_exp_f32_e32 v166, v33
	v_fma_f32 v33, v226, v252, -v229
	v_exp_f32_e32 v167, v33
	s_waitcnt lgkmcnt(2)
	v_mfma_f32_32x32x16_bf16 v[16:31], v[74:77], v[170:173], v[16:31]
	v_cvt_pk_bf16_f32 v76, v62, v63
	v_cvt_pk_bf16_f32 v77, v66, v67
	ds_read_b64_tr_b16 v[66:67], v163 offset:6976
	ds_read_b64_tr_b16 v[68:69], v163 offset:8128
	ds_read_b64_tr_b16 v[170:171], v163 offset:9216
	ds_read_b64_tr_b16 v[172:173], v163 offset:10368
	v_fma_f32 v33, v225, v252, -v229
	v_exp_f32_e32 v72, v33
	v_fma_f32 v33, v227, v252, -v229
	s_waitcnt lgkmcnt(4)
	v_mfma_f32_32x32x16_bf16 v[0:15], v[208:211], v[76:79], v[0:15]
	v_mfma_f32_16x16x32_bf16 v[186:189], v[248:251], v[76:79], v[186:189]
	v_exp_f32_e32 v73, v33
	v_fma_f32 v33, v228, v252, -v229
	v_exp_f32_e32 v74, v33
	v_fma_f32 v33, v230, v252, -v229
	v_exp_f32_e32 v75, v33
	v_fma_f32 v33, v232, v252, -v229
	v_exp_f32_e32 v62, v33
	s_waitcnt lgkmcnt(2)
	v_mfma_f32_32x32x16_bf16 v[16:31], v[66:69], v[76:79], v[16:31]
	v_cvt_pk_bf16_f32 v66, v54, v55
	v_cvt_pk_bf16_f32 v67, v58, v59
	v_cvt_pk_bf16_f32 v68, v60, v61
	v_cvt_pk_bf16_f32 v69, v64, v65
	ds_read_b64_tr_b16 v[58:59], v163 offset:9280
	ds_read_b64_tr_b16 v[60:61], v163 offset:10432
	ds_read_b64_tr_b16 v[76:77], v163 offset:11520
	ds_read_b64_tr_b16 v[78:79], v163 offset:12672
	v_fma_f32 v33, v233, v252, -v229
	s_waitcnt lgkmcnt(4)
	v_mfma_f32_32x32x16_bf16 v[0:15], v[170:173], v[66:69], v[0:15]
	v_mfma_f32_16x16x32_bf16 v[186:189], v[248:251], v[66:69], v[186:189]
	v_exp_f32_e32 v63, v33
	v_fma_f32 v33, v231, v252, -v229
	v_exp_f32_e32 v54, v33
	v_fma_f32 v33, v234, v252, -v229
	v_exp_f32_e32 v55, v33
	v_fma_f32 v33, v235, v252, -v229
	s_waitcnt lgkmcnt(2)
	v_mfma_f32_32x32x16_bf16 v[16:31], v[58:61], v[66:69], v[16:31]
	ds_read_b64_tr_b16 v[56:57], v163 offset:11584
	ds_read_b64_tr_b16 v[58:59], v163 offset:12736
	ds_read_b64_tr_b16 v[64:65], v163 offset:13824
	ds_read_b64_tr_b16 v[66:67], v163 offset:14976
	ds_read_b64_tr_b16 v[42:43], v163 offset:13888
	ds_read_b64_tr_b16 v[44:45], v163 offset:15040
	v_exp_f32_e32 v60, v33
	v_fma_f32 v33, v236, v252, -v229
	v_exp_f32_e32 v61, v33
	v_fma_f32 v33, v237, v252, -v229
	s_waitcnt lgkmcnt(6)
	v_mfma_f32_32x32x16_bf16 v[0:15], v[76:79], v[48:51], v[0:15]
	v_mfma_f32_16x16x32_bf16 v[186:189], v[248:251], v[48:51], v[186:189]
	v_exp_f32_e32 v52, v33
	v_fma_f32 v33, v240, v252, -v229
	v_exp_f32_e32 v53, v33
	v_fma_f32 v33, v239, v252, -v229
	s_waitcnt lgkmcnt(4)
	v_mfma_f32_32x32x16_bf16 v[16:31], v[56:59], v[48:51], v[16:31]
	ds_read_b64_tr_b16 v[46:47], v163 offset:16128
	ds_read_b64_tr_b16 v[48:49], v163 offset:17280
	v_cvt_pk_bf16_f32 v34, v34, v35
	v_cvt_pk_bf16_f32 v35, v36, v37
	v_exp_f32_e32 v50, v33
	v_fma_f32 v33, v241, v252, -v229
	v_exp_f32_e32 v51, v33
	s_waitcnt lgkmcnt(4)
	v_mfma_f32_32x32x16_bf16 v[0:15], v[64:67], v[38:41], v[0:15]
	v_mfma_f32_16x16x32_bf16 v[186:189], v[248:251], v[38:41], v[186:189]
	s_waitcnt lgkmcnt(2)
	v_mfma_f32_32x32x16_bf16 v[16:31], v[42:45], v[38:41], v[16:31]
	v_cvt_pk_bf16_f32 v36, v164, v165
	v_cvt_pk_bf16_f32 v37, v168, v169
	ds_read_b64_tr_b16 v[38:39], v163 offset:16192
	ds_read_b64_tr_b16 v[40:41], v163 offset:17344
	s_waitcnt lgkmcnt(2)
; #define LAS __attribute__((address_space(3)))
; #define MFMA32(a, b, c) __builtin_amdgcn_mfma_f32_32x32x16_bf16((a), (b), (c), 0, 0, 0)
; __device__ __forceinline__ unsigned cvtpk(float lo, float hi) { f32x2_t v = {lo, hi}; bf16x2_t b = __builtin_convertvector(v, bf16x2_t); return __builtin_bit_cast(unsigned, b); }
; __device__ __forceinline__ s16x4 lds_tr(const LAS unsigned char* p) { return __builtin_bit_cast(s16x4, __builtin_amdgcn_ds_read_tr16_b64_v4i16((LAS v4i16_t*)p)); }
; __device__ __forceinline__ void attnA_unit(LAS unsigned char* lds, const Args& A, int unit) {
;     ...
;                 const LAS unsigned char* vr0 = vt_l + (rb + 4 * hh + ((lane & 15) >> 2)) * AST + 32 * ((lane >> 4) & 1) + 8 * (lane & 3);
; #pragma unroll
;                 for (int kt = 0; kt < 5; ++kt)
; #pragma unroll
;                     for (int ks = 0; ks < 2; ++ks) {
;                         const bf16x8 pf = pack_frag(S[kt], ks);
;                         const LAS unsigned char* vr = vr0 + (32 * kt + 16 * ks) * AST;
;                         const s16x4 a0 = lds_tr(vr), a1 = lds_tr(vr + 8 * AST), c0 = lds_tr(vr + 64), c1 = lds_tr(vr + 8 * AST + 64);
;                         o0 = MFMA32(__builtin_shufflevector(a0, a1, 0, 1, 2, 3, 4, 5, 6, 7), pf, o0);
;                         o1 = MFMA32(__builtin_shufflevector(c0, c1, 0, 1, 2, 3, 4, 5, 6, 7), pf, o1);
;                     }
;                 const float inv = 1.0f / ls;
;                 bf16* orow = Qrow + 4 * hh;
; #pragma unroll
;                 for (int g4 = 0; g4 < 4; ++g4) {
;                     u32x2 w; w.x = cvtpk(o0[4 * g4] * inv, o0[4 * g4 + 1] * inv); w.y = cvtpk(o0[4 * g4 + 2] * inv, o0[4 * g4 + 3] * inv); *(u32x2*)(orow + 8 * g4) = w;
;                     u32x2 z; z.x = cvtpk(o1[4 * g4] * inv, o1[4 * g4 + 1] * inv); z.y = cvtpk(o1[4 * g4 + 2] * inv, o1[4 * g4 + 3] * inv); *(u32x2*)(orow + 32 + 8 * g4) = z;
;                 }
;                 if (hh == 0) LSE[(size_t)((g * 4 + b) * 8 + h) * 8192 + pbase + i0 + ql] = mx + __builtin_amdgcn_logf(ls);
	v_mfma_f32_32x32x16_bf16 v[0:15], v[46:49], v[34:37], v[0:15]
	v_mfma_f32_16x16x32_bf16 v[186:189], v[248:251], v[34:37], v[186:189]
	ds_read_b64_tr_b16 v[42:43], v163 offset:18432
	ds_read_b64_tr_b16 v[44:45], v163 offset:19584
	s_waitcnt lgkmcnt(2)
	v_mfma_f32_32x32x16_bf16 v[16:31], v[38:41], v[34:37], v[16:31]
	v_cvt_pk_bf16_f32 v34, v166, v167
	v_cvt_pk_bf16_f32 v35, v72, v73
	v_cvt_pk_bf16_f32 v36, v74, v75
	v_cvt_pk_bf16_f32 v37, v62, v63
	ds_read_b64_tr_b16 v[38:39], v163 offset:18496
	ds_read_b64_tr_b16 v[40:41], v163 offset:19648
	s_waitcnt lgkmcnt(2)
	v_mfma_f32_32x32x16_bf16 v[0:15], v[42:45], v[34:37], v[0:15]
	v_mfma_f32_16x16x32_bf16 v[186:189], v[248:251], v[34:37], v[186:189]
	s_waitcnt lgkmcnt(0)
	v_mfma_f32_32x32x16_bf16 v[16:31], v[38:41], v[34:37], v[16:31]
	ds_read_b64_tr_b16 v[42:43], v163 offset:20736
	ds_read_b64_tr_b16 v[44:45], v163 offset:21888
	ds_read_b64_tr_b16 v[46:47], v163 offset:20800
	ds_read_b64_tr_b16 v[48:49], v163 offset:21952
	v_cvt_pk_bf16_f32 v36, v54, v55
	v_cvt_pk_bf16_f32 v37, v60, v61
	s_waitcnt lgkmcnt(4)
	v_cvt_pk_bf16_f32 v38, v52, v53
	v_cvt_pk_bf16_f32 v39, v50, v51
	v_add3_u32 v40, v162, v144, v32
	v_ashrrev_i32_e32 v41, 31, v40
	s_waitcnt lgkmcnt(2)
	v_mfma_f32_32x32x16_bf16 v[0:15], v[42:45], v[36:39], v[0:15]
	v_mfma_f32_16x16x32_bf16 v[186:189], v[248:251], v[36:39], v[186:189]
	v_lshlrev_b64 v[40:41], 7, v[40:41]
	s_waitcnt lgkmcnt(0)
	v_mfma_f32_32x32x16_bf16 v[16:31], v[46:49], v[36:39], v[16:31]
	s_nop 7
	ds_bpermute_b32 v34, v253, v186
	s_waitcnt lgkmcnt(0)
	v_div_scale_f32 v33, s[22:23], v34, v34, 1.0
	v_rcp_f32_e32 v35, v33
	s_nop 0
	v_fma_f32 v36, -v33, v35, 1.0
	v_fmac_f32_e32 v35, v36, v35
	v_div_scale_f32 v36, vcc, 1.0, v34, 1.0
	v_mul_f32_e32 v37, v36, v35
	v_fma_f32 v38, -v33, v37, v36
	v_fmac_f32_e32 v37, v38, v35
	v_fma_f32 v33, -v33, v37, v36
	v_div_fmas_f32 v33, v33, v35, v37
	v_div_fixup_f32 v36, v33, v34, 1.0
	v_pk_mul_f32 v[0:1], v[36:37], v[0:1] op_sel_hi:[0,1]
	v_pk_mul_f32 v[2:3], v[36:37], v[2:3] op_sel_hi:[0,1]
	v_lshl_add_u64 v[38:39], v[160:161], 0, v[40:41]
	v_cvt_pk_bf16_f32 v0, v0, v1
	v_cvt_pk_bf16_f32 v1, v2, v3
	global_store_dwordx2 v[38:39], v[0:1], off
	v_pk_mul_f32 v[0:1], v[36:37], v[16:17] op_sel_hi:[0,1]
	v_pk_mul_f32 v[2:3], v[36:37], v[18:19] op_sel_hi:[0,1]
	v_cvt_pk_bf16_f32 v0, v0, v1
	v_cvt_pk_bf16_f32 v1, v2, v3
	global_store_dwordx2 v[38:39], v[0:1], off offset:64
	v_pk_mul_f32 v[0:1], v[36:37], v[4:5] op_sel_hi:[0,1]
	v_pk_mul_f32 v[2:3], v[36:37], v[6:7] op_sel_hi:[0,1]
	v_cvt_pk_bf16_f32 v0, v0, v1
	v_cvt_pk_bf16_f32 v1, v2, v3
	global_store_dwordx2 v[38:39], v[0:1], off offset:16
	v_pk_mul_f32 v[0:1], v[36:37], v[20:21] op_sel_hi:[0,1]
	v_pk_mul_f32 v[2:3], v[36:37], v[22:23] op_sel_hi:[0,1]
	v_cvt_pk_bf16_f32 v0, v0, v1
	v_cvt_pk_bf16_f32 v1, v2, v3
	global_store_dwordx2 v[38:39], v[0:1], off offset:80
	v_pk_mul_f32 v[0:1], v[36:37], v[8:9] op_sel_hi:[0,1]
	v_pk_mul_f32 v[2:3], v[36:37], v[10:11] op_sel_hi:[0,1]
	v_cvt_pk_bf16_f32 v0, v0, v1
	v_cvt_pk_bf16_f32 v1, v2, v3
	global_store_dwordx2 v[38:39], v[0:1], off offset:32
	v_pk_mul_f32 v[0:1], v[36:37], v[24:25] op_sel_hi:[0,1]
	v_pk_mul_f32 v[2:3], v[36:37], v[26:27] op_sel_hi:[0,1]
	v_cvt_pk_bf16_f32 v0, v0, v1
	v_cvt_pk_bf16_f32 v1, v2, v3
	global_store_dwordx2 v[38:39], v[0:1], off offset:96
	v_pk_mul_f32 v[0:1], v[36:37], v[12:13] op_sel_hi:[0,1]
	v_pk_mul_f32 v[2:3], v[36:37], v[14:15] op_sel_hi:[0,1]
	v_cvt_pk_bf16_f32 v0, v0, v1
	v_cvt_pk_bf16_f32 v1, v2, v3
	global_store_dwordx2 v[38:39], v[0:1], off offset:48
	v_pk_mul_f32 v[0:1], v[36:37], v[28:29] op_sel_hi:[0,1]
	v_pk_mul_f32 v[2:3], v[36:37], v[30:31] op_sel_hi:[0,1]
	v_cvt_pk_bf16_f32 v0, v0, v1
	v_cvt_pk_bf16_f32 v1, v2, v3
	global_store_dwordx2 v[38:39], v[0:1], off offset:112
	s_and_saveexec_b64 s[22:23], s[6:7]
	s_cbranch_execz .LBB0_303
	v_log_f32_e32 v2, v34
	v_ashrrev_i32_e32 v33, 31, v32
	v_lshl_add_u64 v[0:1], v[32:33], 2, s[80:81]
	v_ashrrev_i32_e32 v163, 31, v162
	v_lshl_add_u64 v[0:1], v[162:163], 2, v[0:1]
	v_lshl_add_u64 v[0:1], v[0:1], 0, v[184:185]
	v_add_f32_e32 v2, v229, v2
	global_store_dword v[0:1], v2, off
